# exp_attndbl
# baseline (speedup 1.0000x reference)
; __device__ __forceinline__ void phase_mixers(const Params& p, int cidx, int layer) {
;   __shared__ int s_item;
;   int* ctr = (int*)(p.ws + WS_CTR) + cidx;
;   constexpr int N_SSM = 128 * (1 + (MIXDBL & 1)), N_POOL = 256 * (1 + ((MIXDBL >> 2) & 1)), N_ATT = 512 * (1 + ((MIXDBL >> 1) & 1));
;   const int n_cv = (layer == 0) ? CV_B * (1 + ((MIXDBL >> 3) & 1)) : 0;
.LBB0_68:
	s_and_b64 vcc, exec, s[8:9]
	s_cbranch_vccz .LBB0_216
	s_cmp_gt_i32 s57, 0
	s_mov_b64 s[8:9], -1
	s_cbranch_scc0 .LBB0_218
	s_lshl_b32 s6, s64, 1
	s_ashr_i32 s7, s6, 31
	s_lshl_b64 s[6:7], s[6:7], 2
	s_add_u32 s6, s86, s6
	s_addc_u32 s7, s87, s7
	s_add_u32 s28, s6, 0x43d10000
	s_addc_u32 s29, s7, 0
	s_add_i32 s6, s44, 4
	s_cmp_lt_u32 s6, 11
	s_movk_i32 s6, 0x824
	v_writelane_b32 v255, s57, 3
	s_cselect_b32 s11, s6, 0x580
	s_mov_b32 s10, s64
	s_ashr_i32 s65, s64, 31
	s_lshl_b32 s8, s64, 10
	v_writelane_b32 v255, s10, 4
	s_lshl_b64 s[6:7], s[64:65], 19
	s_ashr_i32 s9, s8, 31
	v_writelane_b32 v255, s11, 5
	s_lshl_b32 s10, s64, 6
	s_add_u32 s12, s86, 0x10880000
	v_writelane_b32 v255, s12, 6
	s_addc_u32 s12, s87, 0
	v_writelane_b32 v255, s12, 7
	v_readlane_b32 s12, v254, 33
	v_readlane_b32 s18, v254, 39
	v_readlane_b32 s19, v254, 40
	s_add_u32 s12, s18, 0x100000
	v_writelane_b32 v255, s12, 8
	s_addc_u32 s12, s19, 0
	v_readlane_b32 s13, v254, 34
	v_writelane_b32 v255, s12, 9
	s_add_u32 s12, s86, 0x10400000
	v_readlane_b32 s64, v254, 49
	s_addc_u32 s13, s87, 0
	v_readlane_b32 s69, v254, 54
	v_readlane_b32 s74, v254, 59
	v_writelane_b32 v255, s12, 10
	v_readlane_b32 s68, v254, 53
	v_readlane_b32 s75, v254, 60
	s_add_u32 s69, s74, 0x800000
	v_writelane_b32 v255, s13, 11
	s_mov_b32 s68, s10
	s_addc_u32 s10, s75, 0
	v_readlane_b32 s65, v254, 50
	v_readlane_b32 s79, v255, 0
	v_writelane_b32 v255, s10, 12
	s_add_u32 s10, s86, 0xe000000
	s_mov_b32 s65, s11
	s_addc_u32 s11, s87, 0
	v_writelane_b32 v255, s10, 13
	v_readlane_b32 s16, v254, 37
	v_readlane_b32 s17, v254, 38
	v_writelane_b32 v255, s11, 14
	s_add_u32 s10, s80, 0x4000000
	v_writelane_b32 v255, s10, 15
	s_addc_u32 s10, s81, 0
	v_writelane_b32 v255, s10, 16
	s_add_u32 s10, s86, 0x6000000
	s_addc_u32 s11, s87, 0
	v_writelane_b32 v255, s10, 17
	v_readlane_b32 s70, v254, 55
	v_readlane_b32 s71, v254, 56
	v_writelane_b32 v255, s11, 18
	s_add_u32 s10, s16, 0xc000000
	v_writelane_b32 v255, s10, 19
	s_addc_u32 s10, s17, 0
	v_writelane_b32 v255, s10, 20
	s_add_u32 s10, s86, 0x10000000
	s_addc_u32 s11, s87, 0
	v_writelane_b32 v255, s10, 21
	v_readlane_b32 s20, v254, 41
	v_readlane_b32 s78, v254, 63
	v_writelane_b32 v255, s11, 22
	s_add_u32 s10, s86, 0xc000000
	s_addc_u32 s11, s87, 0
	s_add_u32 s70, s86, 0x43d14100
	s_addc_u32 s71, s87, 0
	s_add_u32 s74, s86, 0x14900000
	s_addc_u32 s75, s87, 0
	s_lshl_b64 s[8:9], s[8:9], 2
	v_readlane_b32 s21, v254, 42
	s_add_u32 s78, s20, s8
	s_addc_u32 s79, s21, s9
	v_writelane_b32 v255, s10, 23
	s_add_u32 s12, s86, 0x22900000
	s_addc_u32 s13, s87, 0
	v_writelane_b32 v255, s11, 24
	v_writelane_b32 v255, s12, 25
	v_readlane_b32 s72, v254, 57
	v_readlane_b32 s73, v254, 58
	v_writelane_b32 v255, s13, 26
	s_add_u32 s12, s86, 0x3f900000
	v_writelane_b32 v255, s12, 27
	s_addc_u32 s12, s87, 0
	v_writelane_b32 v255, s12, 28
	s_add_u32 s12, s86, 0x41d00000
	v_writelane_b32 v255, s12, 29
	s_addc_u32 s12, s87, 0
	v_writelane_b32 v255, s12, 30
	s_add_u32 s12, s86, 0x2e900000
	v_writelane_b32 v255, s12, 31
	s_addc_u32 s12, s87, 0
	v_writelane_b32 v255, s12, 32
	s_add_u32 s12, s86, 0x43d00000
	v_writelane_b32 v255, s12, 33
	s_addc_u32 s12, s87, 0
	v_writelane_b32 v255, s12, 34
	s_add_u32 s8, s72, s8
	v_writelane_b32 v255, s8, 35
	s_addc_u32 s8, s73, s9
	s_add_u32 s6, s86, s6
	s_addc_u32 s7, s87, s7
	v_writelane_b32 v255, s8, 36
	s_add_u32 s8, s6, 0x10860000
	s_addc_u32 s9, s7, 0
	v_writelane_b32 v255, s8, 37
	v_readlane_b32 s76, v254, 61
	v_readlane_b32 s66, v254, 51
	v_writelane_b32 v255, s9, 38
	v_writelane_b32 v255, s44, 39
	v_readlane_b32 s67, v254, 52
	v_readlane_b32 s77, v254, 62
	v_writelane_b32 v255, s45, 40
	s_add_u32 s76, s86, 0x3fd03c00
	v_writelane_b32 v255, s46, 41
	s_mov_b64 s[66:67], s[28:29]
	s_mov_b64 s[72:73], s[6:7]
	s_addc_u32 s77, s87, 0
	v_writelane_b32 v255, s47, 42
	v_readlane_b32 s14, v254, 35
	v_readlane_b32 s15, v254, 36
	v_readlane_b32 s22, v254, 43
	v_readlane_b32 s23, v254, 44
	v_readlane_b32 s24, v254, 45
	v_readlane_b32 s25, v254, 46
	v_readlane_b32 s26, v254, 47
	v_readlane_b32 s27, v254, 48
	s_branch .LBB0_73

; __device__ __forceinline__ void phase_mixers(const Params& p, int cidx, int layer) {
;     ...
;     const int it = s_item;
;     if (it >= N_SSM + N_POOL + N_ATT + n_cv) break;
;     if (it < N_SSM) ssm_item(p, layer, it & 127, tidx);
;     else if (it < N_SSM + N_POOL) pool_block_item(p, layer, (it - N_SSM) & 255, tidx);
;     else if (it < N_SSM + N_POOL + N_ATT) attn_wave_item(p, ((it - N_SSM - N_POOL) & 511) * 8 + wid, tidx);
;     else cv_item_B(p, (it - N_SSM - N_POOL - N_ATT) % CV_B, tidx);
.LBB0_77:
	s_or_b64 exec, exec, s[6:7]
	s_waitcnt lgkmcnt(0)
	s_barrier
	ds_read_b32 v0, v163 offset:20
	s_mov_b64 s[6:7], -1
	s_waitcnt lgkmcnt(0)
	v_cmp_le_i32_e32 vcc, s65, v0
	v_readfirstlane_b32 s64, v0
	s_cbranch_vccnz .LBB0_72
	v_ashrrev_i32_e32 v97, 6, v164
	s_cmp_lt_u32 s64, 0x380
	s_cbranch_scc1 .Lid_done
	s_sub_u32 s64, s64, 0x200
